# accumulator zeroing: redundant per-unit zero block skipped on the loop path, remaining zeroing done with v_mov_b64 (all GEMM phases)
# speedup vs baseline: 1.0184x; 1.0080x over previous
; template <class Epi, class Sched, bool ALIGN_EPI = false, bool SP2 = false>
; __device__ __forceinline__ void gemm_phase(PG8_LAS unsigned char* lds, const Gemm g, const Sched& S, const Epi& E) {
;     ...
;     f32x4 acc[2][2][4][2];
; #pragma unroll
;     for (int a = 0; a < 2; ++a)
; #pragma unroll
;         for (int b = 0; b < 2; ++b)
; #pragma unroll
;             for (int m = 0; m < 4; ++m)
; #pragma unroll
;                 for (int n = 0; n < 2; ++n) acc[a][b][m][n] = (f32x4){0.f, 0.f, 0.f, 0.f};
;     bf16x8 At[4][2], B0[2][2], B1[2][2];
;     const char* cA = (const char*)g.A + (size_t)cur.pm * tstepA + (size_t)S.kt0(cur) * (BK * 2); const char* cB = (const char*)g.Bt + (size_t)cur.pn * tstepB + (size_t)S.kt0(cur) * (BK * 2);
;     int ntc = S.ktn(cur, nt);
.LBB0_198:
	s_ashr_i32 s19, s18, 31
	s_lshl_b64 s[20:21], s[18:19], 19
	s_add_u32 s20, s86, s20
	s_addc_u32 s21, s87, s21
	s_ashr_i32 s17, s16, 31
	s_lshl_b64 s[22:23], s[16:17], 19
	s_add_u32 s22, s52, s22
	s_addc_u32 s23, s53, s23
	s_andn2_b64 vcc, exec, s[12:13]
	s_cbranch_vccz .Lzero_skip_ffnup
	v_mov_b32_e32 v161, 0
	v_mov_b32_e32 v160, v161
	v_mov_b32_e32 v159, v161
	v_mov_b32_e32 v158, v161
	v_mov_b32_e32 v153, v161
	v_mov_b32_e32 v152, v161
	v_mov_b32_e32 v151, v161
	v_mov_b32_e32 v150, v161
	v_mov_b32_e32 v145, v161
	v_mov_b32_e32 v144, v161
	v_mov_b32_e32 v143, v161
	v_mov_b32_e32 v142, v161
	v_mov_b32_e32 v137, v161
	v_mov_b32_e32 v136, v161
	v_mov_b32_e32 v135, v161
	v_mov_b32_e32 v134, v161
	v_mov_b32_e32 v125, v161
	v_mov_b32_e32 v124, v161
	v_mov_b32_e32 v123, v161
	v_mov_b32_e32 v122, v161
	v_mov_b32_e32 v93, v161
	v_mov_b32_e32 v92, v161
	v_mov_b32_e32 v91, v161
	v_mov_b32_e32 v90, v161
	v_mov_b32_e32 v81, v161
	v_mov_b32_e32 v80, v161
	v_mov_b32_e32 v79, v161
	v_mov_b32_e32 v78, v161
	v_mov_b32_e32 v73, v161
	v_mov_b32_e32 v72, v161
	v_mov_b32_e32 v71, v161
	v_mov_b32_e32 v70, v161
	v_mov_b32_e32 v157, v161
	v_mov_b32_e32 v156, v161
	v_mov_b32_e32 v155, v161
	v_mov_b32_e32 v154, v161
	v_mov_b32_e32 v149, v161
	v_mov_b32_e32 v148, v161
	v_mov_b32_e32 v147, v161
	v_mov_b32_e32 v146, v161
	v_mov_b32_e32 v141, v161
	v_mov_b32_e32 v140, v161
	v_mov_b32_e32 v139, v161
	v_mov_b32_e32 v138, v161
	v_mov_b32_e32 v133, v161
	v_mov_b32_e32 v132, v161
	v_mov_b32_e32 v131, v161
	v_mov_b32_e32 v130, v161
	v_mov_b32_e32 v117, v161
	v_mov_b32_e32 v116, v161
	v_mov_b32_e32 v115, v161
	v_mov_b32_e32 v114, v161
	v_mov_b32_e32 v85, v161
	v_mov_b32_e32 v84, v161
	v_mov_b32_e32 v83, v161
	v_mov_b32_e32 v82, v161
	v_mov_b32_e32 v77, v161
	v_mov_b32_e32 v76, v161
	v_mov_b32_e32 v75, v161
	v_mov_b32_e32 v74, v161
	v_mov_b32_e32 v69, v161
	v_mov_b32_e32 v68, v161
	v_mov_b32_e32 v67, v161
	v_mov_b32_e32 v66, v161
	v_mov_b32_e32 v63, v161
	v_mov_b32_e32 v62, v161
	v_mov_b32_e32 v61, v161
	v_mov_b32_e32 v60, v161
	v_mov_b32_e32 v55, v161
	v_mov_b32_e32 v54, v161
	v_mov_b32_e32 v53, v161
	v_mov_b32_e32 v52, v161
	v_mov_b32_e32 v47, v161
	v_mov_b32_e32 v46, v161
	v_mov_b32_e32 v45, v161
	v_mov_b32_e32 v44, v161
	v_mov_b32_e32 v39, v161
	v_mov_b32_e32 v38, v161
	v_mov_b32_e32 v37, v161
	v_mov_b32_e32 v36, v161
	v_mov_b32_e32 v31, v161
	v_mov_b32_e32 v30, v161
	v_mov_b32_e32 v29, v161
	v_mov_b32_e32 v28, v161
	v_mov_b32_e32 v23, v161
	v_mov_b32_e32 v22, v161
	v_mov_b32_e32 v21, v161
	v_mov_b32_e32 v20, v161
	v_mov_b32_e32 v15, v161
	v_mov_b32_e32 v14, v161
	v_mov_b32_e32 v13, v161
	v_mov_b32_e32 v12, v161
	v_mov_b32_e32 v7, v161
	v_mov_b32_e32 v6, v161
	v_mov_b32_e32 v5, v161
	v_mov_b32_e32 v4, v161
	v_mov_b32_e32 v59, v161
	v_mov_b32_e32 v58, v161
	v_mov_b32_e32 v57, v161
	v_mov_b32_e32 v56, v161
	v_mov_b32_e32 v51, v161
	v_mov_b32_e32 v50, v161
	v_mov_b32_e32 v49, v161
	v_mov_b32_e32 v48, v161
	v_mov_b32_e32 v43, v161
	v_mov_b32_e32 v42, v161
	v_mov_b32_e32 v41, v161
	v_mov_b32_e32 v40, v161
	v_mov_b32_e32 v35, v161
	v_mov_b32_e32 v34, v161
	v_mov_b32_e32 v33, v161
	v_mov_b32_e32 v32, v161
	v_mov_b32_e32 v27, v161
	v_mov_b32_e32 v26, v161
	v_mov_b32_e32 v25, v161
	v_mov_b32_e32 v24, v161
	v_mov_b32_e32 v19, v161
	v_mov_b32_e32 v18, v161
	v_mov_b32_e32 v17, v161
	v_mov_b32_e32 v16, v161
	v_mov_b32_e32 v11, v161
	v_mov_b32_e32 v10, v161
	v_mov_b32_e32 v9, v161
	v_mov_b32_e32 v8, v161
	v_mov_b32_e32 v3, v161
	v_mov_b32_e32 v2, v161
	v_mov_b32_e32 v1, v161
	v_mov_b32_e32 v0, v161
	s_branch .LBB0_201
.Lzero_skip_ffnup:
	s_and_b64 s[26:27], s[6:7], exec
	s_cselect_b32 s17, s21, s5
	s_cselect_b32 s19, s20, s4
	s_cselect_b32 s43, s23, s25
	s_cselect_b32 s44, s22, s24
	s_add_u32 s4, s4, 0x40080
	s_addc_u32 s5, s5, 0
	s_add_u32 s45, s24, 0x100
	v_mov_b64_e32 v[0:1], 0
	s_addc_u32 s46, s25, 0
	s_mov_b32 s24, 0
	v_mov_b64_e32 v[2:3], 0
	v_mov_b64_e32 v[4:5], 0
	v_mov_b64_e32 v[6:7], 0
	v_mov_b64_e32 v[8:9], 0
	v_mov_b64_e32 v[10:11], 0
	v_mov_b64_e32 v[12:13], 0
	v_mov_b64_e32 v[14:15], 0
	v_mov_b64_e32 v[16:17], 0
	v_mov_b64_e32 v[18:19], 0
	v_mov_b64_e32 v[20:21], 0
	v_mov_b64_e32 v[22:23], 0
	v_mov_b64_e32 v[24:25], 0
	v_mov_b64_e32 v[26:27], 0
	v_mov_b64_e32 v[28:29], 0
	v_mov_b64_e32 v[30:31], 0
	v_mov_b64_e32 v[32:33], 0
	v_mov_b64_e32 v[34:35], 0
	v_mov_b64_e32 v[36:37], 0
	v_mov_b64_e32 v[38:39], 0
	v_mov_b64_e32 v[40:41], 0
	v_mov_b64_e32 v[42:43], 0
	v_mov_b64_e32 v[44:45], 0
	v_mov_b64_e32 v[46:47], 0
	v_mov_b64_e32 v[48:49], 0
	v_mov_b64_e32 v[50:51], 0
	v_mov_b64_e32 v[52:53], 0
	v_mov_b64_e32 v[54:55], 0
	v_mov_b64_e32 v[56:57], 0
	v_mov_b64_e32 v[58:59], 0
	v_mov_b64_e32 v[60:61], 0
	v_mov_b64_e32 v[62:63], 0
	v_mov_b64_e32 v[66:67], 0
	v_mov_b64_e32 v[68:69], 0
	v_mov_b64_e32 v[70:71], 0
	v_mov_b64_e32 v[72:73], 0
	v_mov_b64_e32 v[74:75], 0
	v_mov_b64_e32 v[76:77], 0
	v_mov_b64_e32 v[78:79], 0
	v_mov_b64_e32 v[80:81], 0
	v_mov_b64_e32 v[82:83], 0
	v_mov_b64_e32 v[84:85], 0
	v_mov_b64_e32 v[90:91], 0
	v_mov_b64_e32 v[92:93], 0
	v_mov_b64_e32 v[114:115], 0
	v_mov_b64_e32 v[116:117], 0
	v_mov_b64_e32 v[122:123], 0
	v_mov_b64_e32 v[124:125], 0
	v_mov_b64_e32 v[130:131], 0
	v_mov_b64_e32 v[132:133], 0
	v_mov_b64_e32 v[134:135], 0
	v_mov_b64_e32 v[136:137], 0
	v_mov_b64_e32 v[138:139], 0
	v_mov_b64_e32 v[140:141], 0
	v_mov_b64_e32 v[142:143], 0
	v_mov_b64_e32 v[144:145], 0
	v_mov_b64_e32 v[146:147], 0
	v_mov_b64_e32 v[148:149], 0
	v_mov_b64_e32 v[150:151], 0
	v_mov_b64_e32 v[152:153], 0
	v_mov_b64_e32 v[154:155], 0
	v_mov_b64_e32 v[156:157], 0
	v_mov_b64_e32 v[158:159], 0
	v_mov_b64_e32 v[160:161], 0

; template <class Epi, class Sched, bool ALIGN_EPI = false, bool SP2 = false>
; __device__ __forceinline__ void gemm_phase(PG8_LAS unsigned char* lds, const Gemm g, const Sched& S, const Epi& E) {
;     ...
;         for (int t = 0; t < ntc; t += 2) {
;             const bool last = (t == ntc - 2);
;             const char* a1 = cA + (size_t)(t + 1) * kstep;
;             const char* a2 = last ? nA : cA + (size_t)(t + 2) * kstep; const char* b2 = last ? nB : cB + (size_t)(t + 2) * kstep;
;             const char* a3 = a2 + kstep; const char* b3 = b2 + kstep;
;     ...
;         for (int a = 0; a < 2; ++a)
; #pragma unroll
;             for (int b = 0; b < 2; ++b)
; #pragma unroll
;                 for (int m = 0; m < 4; ++m)
; #pragma unroll
;                     for (int n = 0; n < 2; ++n) acc[a][b][m][n] = (f32x4){0.f, 0.f, 0.f, 0.f};
;         cur = nxt; cA = nA; cB = nB; ++ui; ntc = S.ktn(cur, nt);
.LBB0_276:
	v_mov_b32_e32 v129, 0
	s_andn2_b64 vcc, exec, s[20:21]
	v_mov_b32_e32 v128, 0
	v_mov_b32_e32 v219, 0
	v_mov_b32_e32 v218, 0
	v_mov_b32_e32 v223, 0
	v_mov_b32_e32 v222, 0
	v_mov_b32_e32 v227, 0
	v_mov_b32_e32 v226, 0
	v_mov_b32_e32 v213, 0
	v_mov_b32_e32 v212, 0
	v_mov_b32_e32 v211, 0
	v_mov_b32_e32 v210, 0
	v_mov_b32_e32 v209, 0
	v_mov_b32_e32 v208, 0
	v_mov_b32_e32 v207, 0
	v_mov_b32_e32 v206, 0
	v_mov_b32_e32 v185, 0
	v_mov_b32_e32 v184, 0
	v_mov_b32_e32 v183, 0
	v_mov_b32_e32 v182, 0
	v_mov_b32_e32 v181, 0
	v_mov_b32_e32 v180, 0
	v_mov_b32_e32 v179, 0
	v_mov_b32_e32 v178, 0
	v_mov_b32_e32 v169, 0
	v_mov_b32_e32 v168, 0
	v_mov_b32_e32 v167, 0
	v_mov_b32_e32 v166, 0
	v_mov_b32_e32 v165, 0
	v_mov_b32_e32 v164, 0
	v_mov_b32_e32 v163, 0
	v_mov_b32_e32 v162, 0
	v_mov_b32_e32 v225, 0
	v_mov_b32_e32 v224, 0
	v_mov_b32_e32 v221, 0
	v_mov_b32_e32 v220, 0
	v_mov_b32_e32 v217, 0
	v_mov_b32_e32 v216, 0
	v_mov_b32_e32 v215, 0
	v_mov_b32_e32 v214, 0
	v_mov_b32_e32 v205, 0
	v_mov_b32_e32 v204, 0
	v_mov_b32_e32 v203, 0
	v_mov_b32_e32 v202, 0
	v_mov_b32_e32 v189, 0
	v_mov_b32_e32 v188, 0
	v_mov_b32_e32 v187, 0
	v_mov_b32_e32 v186, 0
	v_mov_b32_e32 v177, 0
	v_mov_b32_e32 v176, 0
	v_mov_b32_e32 v175, 0
	v_mov_b32_e32 v174, 0
	v_mov_b32_e32 v173, 0
	v_mov_b32_e32 v172, 0
	v_mov_b32_e32 v171, 0
	v_mov_b32_e32 v170, 0
	v_mov_b32_e32 v161, 0
	v_mov_b32_e32 v160, 0
	v_mov_b32_e32 v159, 0
	v_mov_b32_e32 v158, 0
	v_mov_b32_e32 v157, 0
	v_mov_b32_e32 v156, 0
	v_mov_b32_e32 v155, 0
	v_mov_b32_e32 v154, 0
	v_mov_b32_e32 v153, 0
	v_mov_b32_e32 v152, 0
	v_mov_b32_e32 v151, 0
	v_mov_b32_e32 v150, 0
	v_mov_b32_e32 v149, 0
	v_mov_b32_e32 v148, 0
	v_mov_b32_e32 v147, 0
	v_mov_b32_e32 v146, 0
	v_mov_b32_e32 v123, 0
	v_mov_b32_e32 v122, 0
	v_mov_b32_e32 v121, 0
	v_mov_b32_e32 v120, 0
	v_mov_b32_e32 v119, 0
	v_mov_b32_e32 v118, 0
	v_mov_b32_e32 v117, 0
	v_mov_b32_e32 v116, 0
	v_mov_b32_e32 v105, 0
	v_mov_b32_e32 v104, 0
	v_mov_b32_e32 v103, 0
	v_mov_b32_e32 v102, 0
	v_mov_b32_e32 v101, 0
	v_mov_b32_e32 v100, 0
	v_mov_b32_e32 v99, 0
	v_mov_b32_e32 v98, 0
	v_mov_b32_e32 v89, 0
	v_mov_b32_e32 v88, 0
	v_mov_b32_e32 v87, 0
	v_mov_b32_e32 v86, 0
	v_mov_b32_e32 v85, 0
	v_mov_b32_e32 v84, 0
	v_mov_b32_e32 v83, 0
	v_mov_b32_e32 v82, 0
	v_mov_b32_e32 v145, 0
	v_mov_b32_e32 v144, 0
	v_mov_b32_e32 v143, 0
	v_mov_b32_e32 v142, 0
	v_mov_b32_e32 v141, 0
	v_mov_b32_e32 v140, 0
	v_mov_b32_e32 v127, 0
	v_mov_b32_e32 v126, 0
	v_mov_b32_e32 v115, 0
	v_mov_b32_e32 v114, 0
	v_mov_b32_e32 v113, 0
	v_mov_b32_e32 v112, 0
	v_mov_b32_e32 v111, 0
	v_mov_b32_e32 v110, 0
	v_mov_b32_e32 v109, 0
	v_mov_b32_e32 v108, 0
	v_mov_b32_e32 v97, 0
	v_mov_b32_e32 v96, 0
	v_mov_b32_e32 v95, 0
	v_mov_b32_e32 v94, 0
	v_mov_b32_e32 v93, 0
	v_mov_b32_e32 v92, 0
	v_mov_b32_e32 v91, 0
	v_mov_b32_e32 v90, 0
	v_mov_b32_e32 v81, 0
	v_mov_b32_e32 v80, 0
	v_mov_b32_e32 v79, 0
	v_mov_b32_e32 v78, 0
	v_mov_b32_e32 v77, 0
	v_mov_b32_e32 v76, 0
	v_mov_b32_e32 v75, 0
	v_mov_b32_e32 v74, 0
	s_cbranch_vccnz .LBB0_280
	s_add_u32 s49, s10, 0x100
	v_mov_b64_e32 v[0:1], 0
	s_addc_u32 s50, s11, 0
	s_mov_b32 s10, 0
	v_mov_b64_e32 v[2:3], 0
	v_mov_b64_e32 v[4:5], 0
	v_mov_b64_e32 v[6:7], 0
	v_mov_b64_e32 v[8:9], 0
	v_mov_b64_e32 v[10:11], 0
	v_mov_b64_e32 v[12:13], 0
	v_mov_b64_e32 v[14:15], 0
	v_mov_b64_e32 v[16:17], 0
	v_mov_b64_e32 v[18:19], 0
	v_mov_b64_e32 v[20:21], 0
	v_mov_b64_e32 v[22:23], 0
	v_mov_b64_e32 v[24:25], 0
	v_mov_b64_e32 v[26:27], 0
	v_mov_b64_e32 v[28:29], 0
	v_mov_b64_e32 v[30:31], 0
	v_mov_b64_e32 v[32:33], 0
	v_mov_b64_e32 v[34:35], 0
	v_mov_b64_e32 v[36:37], 0
	v_mov_b64_e32 v[38:39], 0
	v_mov_b64_e32 v[40:41], 0
	v_mov_b64_e32 v[42:43], 0
	v_mov_b64_e32 v[44:45], 0
	v_mov_b64_e32 v[46:47], 0
	v_mov_b64_e32 v[48:49], 0
	v_mov_b64_e32 v[50:51], 0
	v_mov_b64_e32 v[52:53], 0
	v_mov_b64_e32 v[54:55], 0
	v_mov_b64_e32 v[56:57], 0
	v_mov_b64_e32 v[58:59], 0
	v_mov_b64_e32 v[60:61], 0
	v_mov_b64_e32 v[62:63], 0
	v_mov_b64_e32 v[66:67], 0
	v_mov_b64_e32 v[68:69], 0
	v_mov_b64_e32 v[70:71], 0
	v_mov_b64_e32 v[72:73], 0
	v_mov_b64_e32 v[74:75], 0
	v_mov_b64_e32 v[76:77], 0
	v_mov_b64_e32 v[78:79], 0
	v_mov_b64_e32 v[80:81], 0
	v_mov_b64_e32 v[82:83], 0
	v_mov_b64_e32 v[84:85], 0
	v_mov_b64_e32 v[86:87], 0
	v_mov_b64_e32 v[88:89], 0
	v_mov_b64_e32 v[90:91], 0
	v_mov_b64_e32 v[92:93], 0
	v_mov_b64_e32 v[94:95], 0
	v_mov_b64_e32 v[96:97], 0
	v_mov_b64_e32 v[98:99], 0
	v_mov_b64_e32 v[100:101], 0
	v_mov_b64_e32 v[102:103], 0
	v_mov_b64_e32 v[104:105], 0
	v_mov_b64_e32 v[106:107], 0
	v_mov_b64_e32 v[108:109], 0
	v_mov_b64_e32 v[110:111], 0
	v_mov_b64_e32 v[112:113], 0
	v_mov_b64_e32 v[114:115], 0
	v_mov_b64_e32 v[116:117], 0
	v_mov_b64_e32 v[118:119], 0
	v_mov_b64_e32 v[120:121], 0
	v_mov_b64_e32 v[122:123], 0
	v_mov_b64_e32 v[124:125], 0
	v_mov_b64_e32 v[126:127], 0
	v_mov_b64_e32 v[128:129], 0

; template <class Epi, class Sched, bool ALIGN_EPI = false, bool SP2 = false>
; __device__ __forceinline__ void gemm_phase(PG8_LAS unsigned char* lds, const Gemm g, const Sched& S, const Epi& E) {
;     ...
;         const bool has_next = S.next(ui + 1, nxt);
;         const char* nA = has_next ? (const char*)g.A + (size_t)nxt.pm * tstepA + (size_t)S.kt0(nxt) * (BK * 2) : cA; const char* nB = has_next ? (const char*)g.Bt + (size_t)nxt.pn * tstepB + (size_t)S.kt0(nxt) * (BK * 2) : cB;
;         for (int t = 0; t < ntc; t += 2) {
;             const bool last = (t == ntc - 2);
;             const char* a1 = cA + (size_t)(t + 1) * kstep;
;             const char* a2 = last ? nA : cA + (size_t)(t + 2) * kstep; const char* b2 = last ? nB : cB + (size_t)(t + 2) * kstep;
;             const char* a3 = a2 + kstep; const char* b3 = b2 + kstep;
;     ...
;         for (int a = 0; a < 2; ++a)
; #pragma unroll
;             for (int b = 0; b < 2; ++b)
; #pragma unroll
;                 for (int m = 0; m < 4; ++m)
; #pragma unroll
;                     for (int n = 0; n < 2; ++n) acc[a][b][m][n] = (f32x4){0.f, 0.f, 0.f, 0.f};
;         cur = nxt; cA = nA; cB = nB; ++ui; ntc = S.ktn(cur, nt);
.LBB0_402:
	s_ashr_i32 s19, s18, 31
	s_lshl_b64 s[20:21], s[18:19], 19
	s_add_u32 s20, s86, s20
	s_addc_u32 s21, s87, s21
	s_ashr_i32 s17, s16, 31
	s_lshl_b64 s[22:23], s[16:17], 19
	v_readlane_b32 s17, v255, 5
	s_add_u32 s22, s17, s22
	v_readlane_b32 s17, v255, 6
	s_addc_u32 s23, s17, s23
	s_andn2_b64 vcc, exec, s[12:13]
	s_cbranch_vccz .Lzero_skip_g0
	v_mov_b32_e32 v161, 0
	v_mov_b32_e32 v160, v161
	v_mov_b32_e32 v159, v161
	v_mov_b32_e32 v158, v161
	v_mov_b32_e32 v157, v161
	v_mov_b32_e32 v156, v161
	v_mov_b32_e32 v155, v161
	v_mov_b32_e32 v154, v161
	v_mov_b32_e32 v145, v161
	v_mov_b32_e32 v144, v161
	v_mov_b32_e32 v143, v161
	v_mov_b32_e32 v142, v161
	v_mov_b32_e32 v141, v161
	v_mov_b32_e32 v140, v161
	v_mov_b32_e32 v139, v161
	v_mov_b32_e32 v138, v161
	v_mov_b32_e32 v129, v161
	v_mov_b32_e32 v128, v161
	v_mov_b32_e32 v127, v161
	v_mov_b32_e32 v126, v161
	v_mov_b32_e32 v125, v161
	v_mov_b32_e32 v124, v161
	v_mov_b32_e32 v123, v161
	v_mov_b32_e32 v122, v161
	v_mov_b32_e32 v113, v161
	v_mov_b32_e32 v112, v161
	v_mov_b32_e32 v111, v161
	v_mov_b32_e32 v110, v161
	v_mov_b32_e32 v109, v161
	v_mov_b32_e32 v108, v161
	v_mov_b32_e32 v107, v161
	v_mov_b32_e32 v106, v161
	v_mov_b32_e32 v153, v161
	v_mov_b32_e32 v152, v161
	v_mov_b32_e32 v151, v161
	v_mov_b32_e32 v150, v161
	v_mov_b32_e32 v149, v161
	v_mov_b32_e32 v148, v161
	v_mov_b32_e32 v147, v161
	v_mov_b32_e32 v146, v161
	v_mov_b32_e32 v137, v161
	v_mov_b32_e32 v136, v161
	v_mov_b32_e32 v135, v161
	v_mov_b32_e32 v134, v161
	v_mov_b32_e32 v133, v161
	v_mov_b32_e32 v132, v161
	v_mov_b32_e32 v131, v161
	v_mov_b32_e32 v130, v161
	v_mov_b32_e32 v121, v161
	v_mov_b32_e32 v120, v161
	v_mov_b32_e32 v119, v161
	v_mov_b32_e32 v118, v161
	v_mov_b32_e32 v117, v161
	v_mov_b32_e32 v116, v161
	v_mov_b32_e32 v115, v161
	v_mov_b32_e32 v114, v161
	v_mov_b32_e32 v105, v161
	v_mov_b32_e32 v104, v161
	v_mov_b32_e32 v103, v161
	v_mov_b32_e32 v102, v161
	v_mov_b32_e32 v101, v161
	v_mov_b32_e32 v100, v161
	v_mov_b32_e32 v99, v161
	v_mov_b32_e32 v98, v161
	v_mov_b32_e32 v97, v161
	v_mov_b32_e32 v96, v161
	v_mov_b32_e32 v95, v161
	v_mov_b32_e32 v94, v161
	v_mov_b32_e32 v93, v161
	v_mov_b32_e32 v92, v161
	v_mov_b32_e32 v91, v161
	v_mov_b32_e32 v90, v161
	v_mov_b32_e32 v47, v161
	v_mov_b32_e32 v46, v161
	v_mov_b32_e32 v45, v161
	v_mov_b32_e32 v44, v161
	v_mov_b32_e32 v43, v161
	v_mov_b32_e32 v42, v161
	v_mov_b32_e32 v41, v161
	v_mov_b32_e32 v40, v161
	v_mov_b32_e32 v31, v161
	v_mov_b32_e32 v30, v161
	v_mov_b32_e32 v29, v161
	v_mov_b32_e32 v28, v161
	v_mov_b32_e32 v27, v161
	v_mov_b32_e32 v26, v161
	v_mov_b32_e32 v25, v161
	v_mov_b32_e32 v24, v161
	v_mov_b32_e32 v15, v161
	v_mov_b32_e32 v14, v161
	v_mov_b32_e32 v13, v161
	v_mov_b32_e32 v12, v161
	v_mov_b32_e32 v11, v161
	v_mov_b32_e32 v10, v161
	v_mov_b32_e32 v9, v161
	v_mov_b32_e32 v8, v161
	v_mov_b32_e32 v77, v161
	v_mov_b32_e32 v76, v161
	v_mov_b32_e32 v75, v161
	v_mov_b32_e32 v74, v161
	v_mov_b32_e32 v73, v161
	v_mov_b32_e32 v72, v161
	v_mov_b32_e32 v71, v161
	v_mov_b32_e32 v70, v161
	v_mov_b32_e32 v39, v161
	v_mov_b32_e32 v38, v161
	v_mov_b32_e32 v37, v161
	v_mov_b32_e32 v36, v161
	v_mov_b32_e32 v35, v161
	v_mov_b32_e32 v34, v161
	v_mov_b32_e32 v33, v161
	v_mov_b32_e32 v32, v161
	v_mov_b32_e32 v23, v161
	v_mov_b32_e32 v22, v161
	v_mov_b32_e32 v21, v161
	v_mov_b32_e32 v20, v161
	v_mov_b32_e32 v19, v161
	v_mov_b32_e32 v18, v161
	v_mov_b32_e32 v17, v161
	v_mov_b32_e32 v16, v161
	v_mov_b32_e32 v7, v161
	v_mov_b32_e32 v6, v161
	v_mov_b32_e32 v5, v161
	v_mov_b32_e32 v4, v161
	v_mov_b32_e32 v3, v161
	v_mov_b32_e32 v2, v161
	v_mov_b32_e32 v1, v161
	v_mov_b32_e32 v0, v161
	s_branch .LBB0_405
.Lzero_skip_g0:
	s_and_b64 s[26:27], s[8:9], exec
	s_cselect_b32 s17, s21, s5
	s_cselect_b32 s19, s20, s4
	s_cselect_b32 s43, s23, s25
	s_cselect_b32 s44, s22, s24
	s_add_u32 s4, s4, 0x40080
	s_addc_u32 s5, s5, 0
	s_add_u32 s45, s24, 0x100
	v_mov_b64_e32 v[0:1], 0
	s_addc_u32 s46, s25, 0
	s_mov_b32 s24, 0
	v_mov_b64_e32 v[2:3], 0
	v_mov_b64_e32 v[4:5], 0
	v_mov_b64_e32 v[6:7], 0
	v_mov_b64_e32 v[8:9], 0
	v_mov_b64_e32 v[10:11], 0
	v_mov_b64_e32 v[12:13], 0
	v_mov_b64_e32 v[14:15], 0
	v_mov_b64_e32 v[16:17], 0
	v_mov_b64_e32 v[18:19], 0
	v_mov_b64_e32 v[20:21], 0
	v_mov_b64_e32 v[22:23], 0
	v_mov_b64_e32 v[24:25], 0
	v_mov_b64_e32 v[26:27], 0
	v_mov_b64_e32 v[28:29], 0
	v_mov_b64_e32 v[30:31], 0
	v_mov_b64_e32 v[32:33], 0
	v_mov_b64_e32 v[34:35], 0
	v_mov_b64_e32 v[36:37], 0
	v_mov_b64_e32 v[38:39], 0
	v_mov_b64_e32 v[40:41], 0
	v_mov_b64_e32 v[42:43], 0
	v_mov_b64_e32 v[44:45], 0
	v_mov_b64_e32 v[46:47], 0
	v_mov_b64_e32 v[70:71], 0
	v_mov_b64_e32 v[72:73], 0
	v_mov_b64_e32 v[74:75], 0
	v_mov_b64_e32 v[76:77], 0
	v_mov_b64_e32 v[90:91], 0
	v_mov_b64_e32 v[92:93], 0
	v_mov_b64_e32 v[94:95], 0
	v_mov_b64_e32 v[96:97], 0
	v_mov_b64_e32 v[98:99], 0
	v_mov_b64_e32 v[100:101], 0
	v_mov_b64_e32 v[102:103], 0
	v_mov_b64_e32 v[104:105], 0
	v_mov_b64_e32 v[106:107], 0
	v_mov_b64_e32 v[108:109], 0
	v_mov_b64_e32 v[110:111], 0
	v_mov_b64_e32 v[112:113], 0
	v_mov_b64_e32 v[114:115], 0
	v_mov_b64_e32 v[116:117], 0
	v_mov_b64_e32 v[118:119], 0
	v_mov_b64_e32 v[120:121], 0
	v_mov_b64_e32 v[122:123], 0
	v_mov_b64_e32 v[124:125], 0
	v_mov_b64_e32 v[126:127], 0
	v_mov_b64_e32 v[128:129], 0
	v_mov_b64_e32 v[130:131], 0
	v_mov_b64_e32 v[132:133], 0
	v_mov_b64_e32 v[134:135], 0
	v_mov_b64_e32 v[136:137], 0
	v_mov_b64_e32 v[138:139], 0
	v_mov_b64_e32 v[140:141], 0
	v_mov_b64_e32 v[142:143], 0
	v_mov_b64_e32 v[144:145], 0
	v_mov_b64_e32 v[146:147], 0
	v_mov_b64_e32 v[148:149], 0
	v_mov_b64_e32 v[150:151], 0
	v_mov_b64_e32 v[152:153], 0
	v_mov_b64_e32 v[154:155], 0
	v_mov_b64_e32 v[156:157], 0
	v_mov_b64_e32 v[158:159], 0
	v_mov_b64_e32 v[160:161], 0

; template <class Epi, class Sched, bool ALIGN_EPI = false, bool SP2 = false>
; __device__ __forceinline__ void gemm_phase(PG8_LAS unsigned char* lds, const Gemm g, const Sched& S, const Epi& E) {
;     ...
;         const bool has_next = S.next(ui + 1, nxt);
;         const char* nA = has_next ? (const char*)g.A + (size_t)nxt.pm * tstepA + (size_t)S.kt0(nxt) * (BK * 2) : cA; const char* nB = has_next ? (const char*)g.Bt + (size_t)nxt.pn * tstepB + (size_t)S.kt0(nxt) * (BK * 2) : cB;
;         for (int t = 0; t < ntc; t += 2) {
;             const bool last = (t == ntc - 2);
;             const char* a1 = cA + (size_t)(t + 1) * kstep;
;             const char* a2 = last ? nA : cA + (size_t)(t + 2) * kstep; const char* b2 = last ? nB : cB + (size_t)(t + 2) * kstep;
;             const char* a3 = a2 + kstep; const char* b3 = b2 + kstep;
;     ...
;         for (int a = 0; a < 2; ++a)
; #pragma unroll
;             for (int b = 0; b < 2; ++b)
; #pragma unroll
;                 for (int m = 0; m < 4; ++m)
; #pragma unroll
;                     for (int n = 0; n < 2; ++n) acc[a][b][m][n] = (f32x4){0.f, 0.f, 0.f, 0.f};
;         cur = nxt; cA = nA; cB = nB; ++ui; ntc = S.ktn(cur, nt);
.LBB0_423:
	s_ashr_i32 s19, s18, 31
	s_lshl_b64 s[20:21], s[18:19], 19
	s_add_u32 s20, s35, s20
	s_addc_u32 s21, s36, s21
	s_ashr_i32 s17, s16, 31
	s_lshl_b64 s[22:23], s[16:17], 19
	s_add_u32 s22, s86, s22
	v_mov_b32_e32 v129, 0
	s_addc_u32 s23, s87, s23
	s_andn2_b64 vcc, exec, s[12:13]
	v_mov_b32_e32 v128, v129
	v_mov_b32_e32 v127, v129
	v_mov_b32_e32 v126, v129
	v_mov_b32_e32 v125, v129
	v_mov_b32_e32 v124, v129
	v_mov_b32_e32 v123, v129
	v_mov_b32_e32 v122, v129
	v_mov_b32_e32 v121, v129
	v_mov_b32_e32 v120, v129
	v_mov_b32_e32 v119, v129
	v_mov_b32_e32 v118, v129
	v_mov_b32_e32 v117, v129
	v_mov_b32_e32 v116, v129
	v_mov_b32_e32 v115, v129
	v_mov_b32_e32 v114, v129
	v_mov_b32_e32 v113, v129
	v_mov_b32_e32 v112, v129
	v_mov_b32_e32 v111, v129
	v_mov_b32_e32 v110, v129
	v_mov_b32_e32 v109, v129
	v_mov_b32_e32 v108, v129
	v_mov_b32_e32 v107, v129
	v_mov_b32_e32 v106, v129
	v_mov_b32_e32 v105, v129
	v_mov_b32_e32 v104, v129
	v_mov_b32_e32 v103, v129
	v_mov_b32_e32 v102, v129
	v_mov_b32_e32 v101, v129
	v_mov_b32_e32 v100, v129
	v_mov_b32_e32 v99, v129
	v_mov_b32_e32 v98, v129
	v_mov_b32_e32 v63, v129
	v_mov_b32_e32 v62, v129
	v_mov_b32_e32 v61, v129
	v_mov_b32_e32 v60, v129
	v_mov_b32_e32 v59, v129
	v_mov_b32_e32 v58, v129
	v_mov_b32_e32 v57, v129
	v_mov_b32_e32 v56, v129
	v_mov_b32_e32 v55, v129
	v_mov_b32_e32 v54, v129
	v_mov_b32_e32 v53, v129
	v_mov_b32_e32 v52, v129
	v_mov_b32_e32 v51, v129
	v_mov_b32_e32 v50, v129
	s_waitcnt vmcnt(0)
	v_mov_b32_e32 v49, v129
	v_mov_b32_e32 v48, v129
	v_mov_b32_e32 v47, v129
	v_mov_b32_e32 v46, v129
	v_mov_b32_e32 v45, v129
	v_mov_b32_e32 v44, v129
	v_mov_b32_e32 v43, v129
	v_mov_b32_e32 v42, v129
	v_mov_b32_e32 v41, v129
	v_mov_b32_e32 v40, v129
	v_mov_b32_e32 v39, v129
	v_mov_b32_e32 v38, v129
	v_mov_b32_e32 v37, v129
	v_mov_b32_e32 v36, v129
	v_mov_b32_e32 v35, v129
	v_mov_b32_e32 v34, v129
	v_mov_b32_e32 v33, v129
	v_mov_b32_e32 v32, v129
	v_mov_b32_e32 v97, v129
	v_mov_b32_e32 v96, v129
	v_mov_b32_e32 v95, v129
	v_mov_b32_e32 v94, v129
	v_mov_b32_e32 v93, v129
	v_mov_b32_e32 v92, v129
	v_mov_b32_e32 v91, v129
	v_mov_b32_e32 v90, v129
	v_mov_b32_e32 v89, v129
	v_mov_b32_e32 v88, v129
	v_mov_b32_e32 v87, v129
	v_mov_b32_e32 v86, v129
	v_mov_b32_e32 v85, v129
	v_mov_b32_e32 v84, v129
	v_mov_b32_e32 v83, v129
	v_mov_b32_e32 v82, v129
	v_mov_b32_e32 v81, v129
	v_mov_b32_e32 v80, v129
	v_mov_b32_e32 v79, v129
	v_mov_b32_e32 v78, v129
	v_mov_b32_e32 v77, v129
	v_mov_b32_e32 v76, v129
	v_mov_b32_e32 v75, v129
	v_mov_b32_e32 v74, v129
	v_mov_b32_e32 v73, v129
	v_mov_b32_e32 v72, v129
	v_mov_b32_e32 v71, v129
	v_mov_b32_e32 v70, v129
	v_mov_b32_e32 v69, v129
	v_mov_b32_e32 v68, v129
	v_mov_b32_e32 v67, v129
	v_mov_b32_e32 v66, v129
	v_mov_b32_e32 v31, v129
	v_mov_b32_e32 v30, v129
	v_mov_b32_e32 v29, v129
	v_mov_b32_e32 v28, v129
	v_mov_b32_e32 v27, v129
	v_mov_b32_e32 v26, v129
	v_mov_b32_e32 v25, v129
	v_mov_b32_e32 v24, v129
	v_mov_b32_e32 v23, v129
	v_mov_b32_e32 v22, v129
	v_mov_b32_e32 v21, v129
	v_mov_b32_e32 v20, v129
	v_mov_b32_e32 v19, v129
	v_mov_b32_e32 v18, v129
	v_mov_b32_e32 v17, v129
	v_mov_b32_e32 v16, v129
	v_mov_b32_e32 v15, v129
	v_mov_b32_e32 v14, v129
	v_mov_b32_e32 v13, v129
	v_mov_b32_e32 v12, v129
	v_mov_b32_e32 v11, v129
	v_mov_b32_e32 v10, v129
	v_mov_b32_e32 v9, v129
	v_mov_b32_e32 v8, v129
	v_mov_b32_e32 v7, v129
	v_mov_b32_e32 v6, v129
	v_mov_b32_e32 v5, v129
	v_mov_b32_e32 v4, v129
	v_mov_b32_e32 v3, v129
	v_mov_b32_e32 v2, v129
	s_waitcnt lgkmcnt(0)
	v_mov_b32_e32 v1, v129
	v_mov_b32_e32 v0, v129
	s_cbranch_vccnz .LBB0_426
	s_and_b64 s[30:31], s[6:7], exec
	s_cselect_b32 s2, s21, s27
	s_cselect_b32 s5, s20, s26
	s_cselect_b32 s17, s23, s29
	s_cselect_b32 s19, s22, s28
	s_add_u32 s26, s26, 0x40080
	s_addc_u32 s27, s27, 0
	s_add_u32 s25, s28, 0x100
	v_mov_b64_e32 v[0:1], 0
	s_addc_u32 s50, s29, 0
	s_mov_b32 s28, 0
	v_mov_b64_e32 v[2:3], 0
	v_mov_b64_e32 v[4:5], 0
	v_mov_b64_e32 v[6:7], 0
	v_mov_b64_e32 v[8:9], 0
	v_mov_b64_e32 v[10:11], 0
	v_mov_b64_e32 v[12:13], 0
	v_mov_b64_e32 v[14:15], 0
	v_mov_b64_e32 v[16:17], 0
	v_mov_b64_e32 v[18:19], 0
	v_mov_b64_e32 v[20:21], 0
	v_mov_b64_e32 v[22:23], 0
	v_mov_b64_e32 v[24:25], 0
	v_mov_b64_e32 v[26:27], 0
	v_mov_b64_e32 v[28:29], 0
	v_mov_b64_e32 v[30:31], 0
	v_mov_b64_e32 v[32:33], 0
	v_mov_b64_e32 v[34:35], 0
	v_mov_b64_e32 v[36:37], 0
	v_mov_b64_e32 v[38:39], 0
	v_mov_b64_e32 v[40:41], 0
	v_mov_b64_e32 v[42:43], 0
	v_mov_b64_e32 v[44:45], 0
	v_mov_b64_e32 v[46:47], 0
	v_mov_b64_e32 v[48:49], 0
	v_mov_b64_e32 v[50:51], 0
	v_mov_b64_e32 v[52:53], 0
	v_mov_b64_e32 v[54:55], 0
	v_mov_b64_e32 v[56:57], 0
	v_mov_b64_e32 v[58:59], 0
	v_mov_b64_e32 v[60:61], 0
	v_mov_b64_e32 v[62:63], 0
	v_mov_b64_e32 v[66:67], 0
	v_mov_b64_e32 v[68:69], 0
	v_mov_b64_e32 v[70:71], 0
	v_mov_b64_e32 v[72:73], 0
	v_mov_b64_e32 v[74:75], 0
	v_mov_b64_e32 v[76:77], 0
	v_mov_b64_e32 v[78:79], 0
	v_mov_b64_e32 v[80:81], 0
	v_mov_b64_e32 v[82:83], 0
	v_mov_b64_e32 v[84:85], 0
	v_mov_b64_e32 v[86:87], 0
	v_mov_b64_e32 v[88:89], 0
	v_mov_b64_e32 v[90:91], 0
	v_mov_b64_e32 v[92:93], 0
	v_mov_b64_e32 v[94:95], 0
	v_mov_b64_e32 v[96:97], 0
	v_mov_b64_e32 v[98:99], 0
	v_mov_b64_e32 v[100:101], 0
	v_mov_b64_e32 v[102:103], 0
	v_mov_b64_e32 v[104:105], 0
	v_mov_b64_e32 v[106:107], 0
	v_mov_b64_e32 v[108:109], 0
	v_mov_b64_e32 v[110:111], 0
	v_mov_b64_e32 v[112:113], 0
	v_mov_b64_e32 v[114:115], 0
	v_mov_b64_e32 v[116:117], 0
	v_mov_b64_e32 v[118:119], 0
	v_mov_b64_e32 v[120:121], 0
	v_mov_b64_e32 v[122:123], 0
	v_mov_b64_e32 v[124:125], 0
	v_mov_b64_e32 v[126:127], 0
	v_mov_b64_e32 v[128:129], 0

; template <class Epi, class Sched, bool ALIGN_EPI = false, bool SP2 = false>
; __device__ __forceinline__ void gemm_phase(PG8_LAS unsigned char* lds, const Gemm g, const Sched& S, const Epi& E) {
;     ...
;         const bool has_next = S.next(ui + 1, nxt);
;         const char* nA = has_next ? (const char*)g.A + (size_t)nxt.pm * tstepA + (size_t)S.kt0(nxt) * (BK * 2) : cA; const char* nB = has_next ? (const char*)g.Bt + (size_t)nxt.pn * tstepB + (size_t)S.kt0(nxt) * (BK * 2) : cB;
;         for (int t = 0; t < ntc; t += 2) {
;             const bool last = (t == ntc - 2);
;             const char* a1 = cA + (size_t)(t + 1) * kstep;
;             const char* a2 = last ? nA : cA + (size_t)(t + 2) * kstep; const char* b2 = last ? nB : cB + (size_t)(t + 2) * kstep;
;             const char* a3 = a2 + kstep; const char* b3 = b2 + kstep;
;     ...
;         for (int a = 0; a < 2; ++a)
; #pragma unroll
;             for (int b = 0; b < 2; ++b)
; #pragma unroll
;                 for (int m = 0; m < 4; ++m)
; #pragma unroll
;                     for (int n = 0; n < 2; ++n) acc[a][b][m][n] = (f32x4){0.f, 0.f, 0.f, 0.f};
;         cur = nxt; cA = nA; cB = nB; ++ui; ntc = S.ktn(cur, nt);
.LBB0_652:
	s_ashr_i32 s17, s16, 31
	s_lshl_b64 s[18:19], s[16:17], 19
	s_add_u32 s18, s80, s18
	s_addc_u32 s19, s81, s19
	s_ashr_i32 s15, s14, 31
	s_lshl_b64 s[20:21], s[14:15], 19
	s_add_u32 s20, s27, s20
	v_mov_b32_e32 v125, 0
	s_addc_u32 s21, s28, s21
	s_andn2_b64 vcc, exec, s[10:11]
	v_mov_b32_e32 v124, v125
	v_mov_b32_e32 v123, v125
	v_mov_b32_e32 v122, v125
	v_mov_b32_e32 v129, v125
	v_mov_b32_e32 v128, v125
	v_mov_b32_e32 v127, v125
	v_mov_b32_e32 v126, v125
	v_mov_b32_e32 v113, v125
	v_mov_b32_e32 v112, v125
	v_mov_b32_e32 v111, v125
	v_mov_b32_e32 v110, v125
	v_mov_b32_e32 v109, v125
	v_mov_b32_e32 v108, v125
	v_mov_b32_e32 v107, v125
	v_mov_b32_e32 v106, v125
	v_mov_b32_e32 v97, v125
	v_mov_b32_e32 v96, v125
	v_mov_b32_e32 v95, v125
	v_mov_b32_e32 v94, v125
	v_mov_b32_e32 v93, v125
	v_mov_b32_e32 v92, v125
	v_mov_b32_e32 v91, v125
	v_mov_b32_e32 v90, v125
	v_mov_b32_e32 v81, v125
	v_mov_b32_e32 v80, v125
	v_mov_b32_e32 v79, v125
	v_mov_b32_e32 v78, v125
	v_mov_b32_e32 v77, v125
	v_mov_b32_e32 v76, v125
	v_mov_b32_e32 v75, v125
	v_mov_b32_e32 v74, v125
	v_mov_b32_e32 v121, v125
	v_mov_b32_e32 v120, v125
	v_mov_b32_e32 v119, v125
	v_mov_b32_e32 v118, v125
	v_mov_b32_e32 v117, v125
	v_mov_b32_e32 v116, v125
	v_mov_b32_e32 v115, v125
	v_mov_b32_e32 v114, v125
	v_mov_b32_e32 v105, v125
	v_mov_b32_e32 v104, v125
	v_mov_b32_e32 v103, v125
	v_mov_b32_e32 v102, v125
	v_mov_b32_e32 v101, v125
	v_mov_b32_e32 v100, v125
	v_mov_b32_e32 v99, v125
	v_mov_b32_e32 v98, v125
	v_mov_b32_e32 v89, v125
	v_mov_b32_e32 v88, v125
	v_mov_b32_e32 v87, v125
	v_mov_b32_e32 v86, v125
	v_mov_b32_e32 v85, v125
	v_mov_b32_e32 v84, v125
	v_mov_b32_e32 v83, v125
	v_mov_b32_e32 v82, v125
	v_mov_b32_e32 v73, v125
	v_mov_b32_e32 v72, v125
	v_mov_b32_e32 v71, v125
	v_mov_b32_e32 v70, v125
	v_mov_b32_e32 v69, v125
	v_mov_b32_e32 v68, v125
	v_mov_b32_e32 v67, v125
	v_mov_b32_e32 v66, v125
	v_mov_b32_e32 v63, v125
	v_mov_b32_e32 v62, v125
	v_mov_b32_e32 v61, v125
	v_mov_b32_e32 v60, v125
	v_mov_b32_e32 v59, v125
	v_mov_b32_e32 v58, v125
	v_mov_b32_e32 v57, v125
	v_mov_b32_e32 v56, v125
	s_waitcnt vmcnt(0)
	v_mov_b32_e32 v47, v125
	v_mov_b32_e32 v46, v125
	v_mov_b32_e32 v45, v125
	v_mov_b32_e32 v44, v125
	v_mov_b32_e32 v43, v125
	v_mov_b32_e32 v42, v125
	v_mov_b32_e32 v41, v125
	v_mov_b32_e32 v40, v125
	v_mov_b32_e32 v31, v125
	v_mov_b32_e32 v30, v125
	v_mov_b32_e32 v29, v125
	v_mov_b32_e32 v28, v125
	v_mov_b32_e32 v27, v125
	v_mov_b32_e32 v26, v125
	v_mov_b32_e32 v25, v125
	v_mov_b32_e32 v24, v125
	v_mov_b32_e32 v15, v125
	v_mov_b32_e32 v14, v125
	v_mov_b32_e32 v13, v125
	v_mov_b32_e32 v12, v125
	v_mov_b32_e32 v11, v125
	v_mov_b32_e32 v10, v125
	v_mov_b32_e32 v9, v125
	v_mov_b32_e32 v8, v125
	v_mov_b32_e32 v55, v125
	v_mov_b32_e32 v54, v125
	v_mov_b32_e32 v53, v125
	v_mov_b32_e32 v52, v125
	v_mov_b32_e32 v51, v125
	v_mov_b32_e32 v50, v125
	v_mov_b32_e32 v49, v125
	v_mov_b32_e32 v48, v125
	v_mov_b32_e32 v39, v125
	v_mov_b32_e32 v38, v125
	v_mov_b32_e32 v37, v125
	v_mov_b32_e32 v36, v125
	v_mov_b32_e32 v35, v125
	v_mov_b32_e32 v34, v125
	v_mov_b32_e32 v33, v125
	v_mov_b32_e32 v32, v125
	v_mov_b32_e32 v23, v125
	v_mov_b32_e32 v22, v125
	v_mov_b32_e32 v21, v125
	v_mov_b32_e32 v20, v125
	v_mov_b32_e32 v19, v125
	v_mov_b32_e32 v18, v125
	v_mov_b32_e32 v17, v125
	v_mov_b32_e32 v16, v125
	v_mov_b32_e32 v7, v125
	v_mov_b32_e32 v6, v125
	v_mov_b32_e32 v5, v125
	v_mov_b32_e32 v4, v125
	v_mov_b32_e32 v3, v125
	v_mov_b32_e32 v2, v125
	v_mov_b32_e32 v1, v125
	v_mov_b32_e32 v0, v125
	s_cbranch_vccnz .LBB0_655
	s_and_b64 s[24:25], s[6:7], exec
	s_cselect_b32 s15, s19, s5
	s_cselect_b32 s17, s18, s4
	s_cselect_b32 s45, s21, s23
	s_cselect_b32 s46, s20, s22
	s_add_u32 s4, s4, 0x40080
	s_addc_u32 s5, s5, 0
	s_add_u32 s47, s22, 0x100
	v_mov_b64_e32 v[0:1], 0
	s_addc_u32 s48, s23, 0
	s_mov_b32 s22, 0
	v_mov_b64_e32 v[2:3], 0
	v_mov_b64_e32 v[4:5], 0
	v_mov_b64_e32 v[6:7], 0
	v_mov_b64_e32 v[8:9], 0
	v_mov_b64_e32 v[10:11], 0
	v_mov_b64_e32 v[12:13], 0
	v_mov_b64_e32 v[14:15], 0
	v_mov_b64_e32 v[16:17], 0
	v_mov_b64_e32 v[18:19], 0
	v_mov_b64_e32 v[20:21], 0
	v_mov_b64_e32 v[22:23], 0
	v_mov_b64_e32 v[24:25], 0
	v_mov_b64_e32 v[26:27], 0
	v_mov_b64_e32 v[28:29], 0
	v_mov_b64_e32 v[30:31], 0
	v_mov_b64_e32 v[32:33], 0
	v_mov_b64_e32 v[34:35], 0
	v_mov_b64_e32 v[36:37], 0
	v_mov_b64_e32 v[38:39], 0
	v_mov_b64_e32 v[40:41], 0
	v_mov_b64_e32 v[42:43], 0
	v_mov_b64_e32 v[44:45], 0
	v_mov_b64_e32 v[46:47], 0
	v_mov_b64_e32 v[48:49], 0
	v_mov_b64_e32 v[50:51], 0
	v_mov_b64_e32 v[52:53], 0
	v_mov_b64_e32 v[54:55], 0
	v_mov_b64_e32 v[56:57], 0
	v_mov_b64_e32 v[58:59], 0
	v_mov_b64_e32 v[60:61], 0
	v_mov_b64_e32 v[62:63], 0
	v_mov_b64_e32 v[66:67], 0
	v_mov_b64_e32 v[68:69], 0
	v_mov_b64_e32 v[70:71], 0
	v_mov_b64_e32 v[72:73], 0
	v_mov_b64_e32 v[74:75], 0
	v_mov_b64_e32 v[76:77], 0
	v_mov_b64_e32 v[78:79], 0
	v_mov_b64_e32 v[80:81], 0
	v_mov_b64_e32 v[82:83], 0
	v_mov_b64_e32 v[84:85], 0
	v_mov_b64_e32 v[86:87], 0
	v_mov_b64_e32 v[88:89], 0
	v_mov_b64_e32 v[90:91], 0
	v_mov_b64_e32 v[92:93], 0
	v_mov_b64_e32 v[94:95], 0
	v_mov_b64_e32 v[96:97], 0
	v_mov_b64_e32 v[98:99], 0
	v_mov_b64_e32 v[100:101], 0
	v_mov_b64_e32 v[102:103], 0
	v_mov_b64_e32 v[104:105], 0
	v_mov_b64_e32 v[106:107], 0
	v_mov_b64_e32 v[108:109], 0
	v_mov_b64_e32 v[110:111], 0
	v_mov_b64_e32 v[112:113], 0
	v_mov_b64_e32 v[114:115], 0
	v_mov_b64_e32 v[116:117], 0
	v_mov_b64_e32 v[118:119], 0
	v_mov_b64_e32 v[120:121], 0
	v_mov_b64_e32 v[122:123], 0
	v_mov_b64_e32 v[124:125], 0
	v_mov_b64_e32 v[126:127], 0
	v_mov_b64_e32 v[128:129], 0

; template <class Epi, class Sched, bool ALIGN_EPI = false, bool SP2 = false>
; __device__ __forceinline__ void gemm_phase(PG8_LAS unsigned char* lds, const Gemm g, const Sched& S, const Epi& E) {
;     ...
;         const bool has_next = S.next(ui + 1, nxt);
;         const char* nA = has_next ? (const char*)g.A + (size_t)nxt.pm * tstepA + (size_t)S.kt0(nxt) * (BK * 2) : cA; const char* nB = has_next ? (const char*)g.Bt + (size_t)nxt.pn * tstepB + (size_t)S.kt0(nxt) * (BK * 2) : cB;
;         for (int t = 0; t < ntc; t += 2) {
;             const bool last = (t == ntc - 2);
;             const char* a1 = cA + (size_t)(t + 1) * kstep;
;             const char* a2 = last ? nA : cA + (size_t)(t + 2) * kstep; const char* b2 = last ? nB : cB + (size_t)(t + 2) * kstep;
;             const char* a3 = a2 + kstep; const char* b3 = b2 + kstep;
;     ...
;         for (int a = 0; a < 2; ++a)
; #pragma unroll
;             for (int b = 0; b < 2; ++b)
; #pragma unroll
;                 for (int m = 0; m < 4; ++m)
; #pragma unroll
;                     for (int n = 0; n < 2; ++n) acc[a][b][m][n] = (f32x4){0.f, 0.f, 0.f, 0.f};
;         cur = nxt; cA = nA; cB = nB; ++ui; ntc = S.ktn(cur, nt);
.LBB0_744:
	s_ashr_i32 s21, s20, 31
	s_lshl_b64 s[10:11], s[20:21], 19
	s_add_u32 s22, s86, s10
	s_addc_u32 s23, s87, s11
	s_ashr_i32 s19, s18, 31
	s_lshl_b64 s[10:11], s[18:19], 19
	s_add_u32 s24, s54, s10
	s_addc_u32 s25, s55, s11
	s_andn2_b64 vcc, exec, s[14:15]
	s_cbranch_vccz .Lzero_skip_g1
	v_mov_b32_e32 v161, 0
	v_mov_b32_e32 v160, v161
	v_mov_b32_e32 v159, v161
	v_mov_b32_e32 v158, v161
	v_mov_b32_e32 v157, v161
	v_mov_b32_e32 v156, v161
	v_mov_b32_e32 v155, v161
	v_mov_b32_e32 v154, v161
	v_mov_b32_e32 v145, v161
	v_mov_b32_e32 v144, v161
	v_mov_b32_e32 v143, v161
	v_mov_b32_e32 v142, v161
	v_mov_b32_e32 v141, v161
	v_mov_b32_e32 v140, v161
	v_mov_b32_e32 v139, v161
	v_mov_b32_e32 v138, v161
	v_mov_b32_e32 v125, v161
	v_mov_b32_e32 v124, v161
	v_mov_b32_e32 v123, v161
	v_mov_b32_e32 v122, v161
	v_mov_b32_e32 v113, v161
	v_mov_b32_e32 v112, v161
	v_mov_b32_e32 v111, v161
	v_mov_b32_e32 v110, v161
	v_mov_b32_e32 v81, v161
	v_mov_b32_e32 v80, v161
	v_mov_b32_e32 v79, v161
	v_mov_b32_e32 v78, v161
	v_mov_b32_e32 v77, v161
	v_mov_b32_e32 v76, v161
	v_mov_b32_e32 v75, v161
	v_mov_b32_e32 v74, v161
	v_mov_b32_e32 v153, v161
	v_mov_b32_e32 v152, v161
	v_mov_b32_e32 v151, v161
	v_mov_b32_e32 v150, v161
	v_mov_b32_e32 v149, v161
	v_mov_b32_e32 v148, v161
	v_mov_b32_e32 v147, v161
	v_mov_b32_e32 v146, v161
	v_mov_b32_e32 v137, v161
	v_mov_b32_e32 v136, v161
	v_mov_b32_e32 v135, v161
	v_mov_b32_e32 v134, v161
	v_mov_b32_e32 v133, v161
	v_mov_b32_e32 v132, v161
	v_mov_b32_e32 v131, v161
	v_mov_b32_e32 v130, v161
	v_mov_b32_e32 v89, v161
	v_mov_b32_e32 v88, v161
	v_mov_b32_e32 v87, v161
	v_mov_b32_e32 v86, v161
	v_mov_b32_e32 v85, v161
	v_mov_b32_e32 v84, v161
	v_mov_b32_e32 v83, v161
	v_mov_b32_e32 v82, v161
	v_mov_b32_e32 v73, v161
	v_mov_b32_e32 v72, v161
	v_mov_b32_e32 v71, v161
	v_mov_b32_e32 v70, v161
	v_mov_b32_e32 v69, v161
	v_mov_b32_e32 v68, v161
	v_mov_b32_e32 v67, v161
	v_mov_b32_e32 v66, v161
	v_mov_b32_e32 v63, v161
	v_mov_b32_e32 v62, v161
	v_mov_b32_e32 v61, v161
	v_mov_b32_e32 v60, v161
	v_mov_b32_e32 v59, v161
	v_mov_b32_e32 v58, v161
	v_mov_b32_e32 v57, v161
	v_mov_b32_e32 v56, v161
	v_mov_b32_e32 v47, v161
	v_mov_b32_e32 v46, v161
	v_mov_b32_e32 v45, v161
	v_mov_b32_e32 v44, v161
	v_mov_b32_e32 v43, v161
	v_mov_b32_e32 v42, v161
	v_mov_b32_e32 v41, v161
	v_mov_b32_e32 v40, v161
	v_mov_b32_e32 v31, v161
	v_mov_b32_e32 v30, v161
	v_mov_b32_e32 v29, v161
	v_mov_b32_e32 v28, v161
	v_mov_b32_e32 v27, v161
	v_mov_b32_e32 v26, v161
	v_mov_b32_e32 v25, v161
	v_mov_b32_e32 v24, v161
	v_mov_b32_e32 v15, v161
	v_mov_b32_e32 v14, v161
	v_mov_b32_e32 v13, v161
	v_mov_b32_e32 v12, v161
	v_mov_b32_e32 v11, v161
	v_mov_b32_e32 v10, v161
	v_mov_b32_e32 v9, v161
	v_mov_b32_e32 v8, v161
	v_mov_b32_e32 v55, v161
	v_mov_b32_e32 v54, v161
	v_mov_b32_e32 v53, v161
	v_mov_b32_e32 v52, v161
	v_mov_b32_e32 v51, v161
	v_mov_b32_e32 v50, v161
	v_mov_b32_e32 v49, v161
	v_mov_b32_e32 v48, v161
	v_mov_b32_e32 v39, v161
	v_mov_b32_e32 v38, v161
	v_mov_b32_e32 v37, v161
	v_mov_b32_e32 v36, v161
	v_mov_b32_e32 v35, v161
	v_mov_b32_e32 v34, v161
	v_mov_b32_e32 v33, v161
	v_mov_b32_e32 v32, v161
	v_mov_b32_e32 v23, v161
	v_mov_b32_e32 v22, v161
	v_mov_b32_e32 v21, v161
	v_mov_b32_e32 v20, v161
	v_mov_b32_e32 v19, v161
	v_mov_b32_e32 v18, v161
	v_mov_b32_e32 v17, v161
	v_mov_b32_e32 v16, v161
	v_mov_b32_e32 v7, v161
	v_mov_b32_e32 v6, v161
	v_mov_b32_e32 v5, v161
	v_mov_b32_e32 v4, v161
	v_mov_b32_e32 v3, v161
	v_mov_b32_e32 v2, v161
	v_mov_b32_e32 v1, v161
	v_mov_b32_e32 v0, v161
	s_branch .LBB0_747
.Lzero_skip_g1:
	s_and_b64 s[10:11], s[6:7], exec
	s_cselect_b32 s19, s23, s5
	s_cselect_b32 s21, s22, s4
	s_cselect_b32 s27, s25, s9
	s_cselect_b32 s28, s24, s8
	s_add_u32 s4, s4, 0x40080
	s_addc_u32 s5, s5, 0
	s_add_u32 s29, s8, 0x100
	v_mov_b64_e32 v[0:1], 0
	s_addc_u32 s30, s9, 0
	s_mov_b32 s8, 0
	v_mov_b64_e32 v[2:3], 0
	v_mov_b64_e32 v[4:5], 0
	v_mov_b64_e32 v[6:7], 0
	v_mov_b64_e32 v[8:9], 0
	v_mov_b64_e32 v[10:11], 0
	v_mov_b64_e32 v[12:13], 0
	v_mov_b64_e32 v[14:15], 0
	v_mov_b64_e32 v[16:17], 0
	v_mov_b64_e32 v[18:19], 0
	v_mov_b64_e32 v[20:21], 0
	v_mov_b64_e32 v[22:23], 0
	v_mov_b64_e32 v[24:25], 0
	v_mov_b64_e32 v[26:27], 0
	v_mov_b64_e32 v[28:29], 0
	v_mov_b64_e32 v[30:31], 0
	v_mov_b64_e32 v[32:33], 0
	v_mov_b64_e32 v[34:35], 0
	v_mov_b64_e32 v[36:37], 0
	v_mov_b64_e32 v[38:39], 0
	v_mov_b64_e32 v[40:41], 0
	v_mov_b64_e32 v[42:43], 0
	v_mov_b64_e32 v[44:45], 0
	v_mov_b64_e32 v[46:47], 0
	v_mov_b64_e32 v[48:49], 0
	v_mov_b64_e32 v[50:51], 0
	v_mov_b64_e32 v[52:53], 0
	v_mov_b64_e32 v[54:55], 0
	v_mov_b64_e32 v[56:57], 0
	v_mov_b64_e32 v[58:59], 0
	v_mov_b64_e32 v[60:61], 0
	v_mov_b64_e32 v[62:63], 0
	v_mov_b64_e32 v[66:67], 0
	v_mov_b64_e32 v[68:69], 0
	v_mov_b64_e32 v[70:71], 0
	v_mov_b64_e32 v[72:73], 0
	v_mov_b64_e32 v[74:75], 0
	v_mov_b64_e32 v[76:77], 0
	v_mov_b64_e32 v[78:79], 0
	v_mov_b64_e32 v[80:81], 0
	v_mov_b64_e32 v[82:83], 0
	v_mov_b64_e32 v[84:85], 0
	v_mov_b64_e32 v[86:87], 0
	v_mov_b64_e32 v[88:89], 0
	v_mov_b64_e32 v[110:111], 0
	v_mov_b64_e32 v[112:113], 0
	v_mov_b64_e32 v[122:123], 0
	v_mov_b64_e32 v[124:125], 0
	v_mov_b64_e32 v[130:131], 0
	v_mov_b64_e32 v[132:133], 0
	v_mov_b64_e32 v[134:135], 0
	v_mov_b64_e32 v[136:137], 0
	v_mov_b64_e32 v[138:139], 0
	v_mov_b64_e32 v[140:141], 0
	v_mov_b64_e32 v[142:143], 0
	v_mov_b64_e32 v[144:145], 0
	v_mov_b64_e32 v[146:147], 0
	v_mov_b64_e32 v[148:149], 0
	v_mov_b64_e32 v[150:151], 0
	v_mov_b64_e32 v[152:153], 0
	v_mov_b64_e32 v[154:155], 0
	v_mov_b64_e32 v[156:157], 0
	v_mov_b64_e32 v[158:159], 0
	v_mov_b64_e32 v[160:161], 0

; template <class Epi, class Sched, bool ALIGN_EPI = false, bool SP2 = false>
; __device__ __forceinline__ void gemm_phase(PG8_LAS unsigned char* lds, const Gemm g, const Sched& S, const Epi& E) {
;     ...
;         const char* nA = has_next ? (const char*)g.A + (size_t)nxt.pm * tstepA + (size_t)S.kt0(nxt) * (BK * 2) : cA; const char* nB = has_next ? (const char*)g.Bt + (size_t)nxt.pn * tstepB + (size_t)S.kt0(nxt) * (BK * 2) : cB;
;         for (int t = 0; t < ntc; t += 2) {
;             const bool last = (t == ntc - 2);
;             const char* a1 = cA + (size_t)(t + 1) * kstep;
;             const char* a2 = last ? nA : cA + (size_t)(t + 2) * kstep; const char* b2 = last ? nB : cB + (size_t)(t + 2) * kstep;
;             const char* a3 = a2 + kstep; const char* b3 = b2 + kstep;
;     ...
;         for (int a = 0; a < 2; ++a)
; #pragma unroll
;             for (int b = 0; b < 2; ++b)
; #pragma unroll
;                 for (int m = 0; m < 4; ++m)
; #pragma unroll
;                     for (int n = 0; n < 2; ++n) acc[a][b][m][n] = (f32x4){0.f, 0.f, 0.f, 0.f};
;         cur = nxt; cA = nA; cB = nB; ++ui; ntc = S.ktn(cur, nt);
.LBB0_904:
	s_ashr_i32 s13, s12, 31
	s_lshl_b64 s[22:23], s[12:13], 19
	s_add_u32 s13, s0, s22
	s_addc_u32 s17, s1, s23
	s_add_u32 s16, s13, s16
	s_addc_u32 s17, s17, 0
	s_and_b64 s[22:23], s[8:9], exec
	s_cselect_b32 s13, s17, s19
	s_cselect_b32 s44, s16, s18
	s_add_i32 s45, s43, -2
	s_add_u32 s18, s18, 0x40080
	s_addc_u32 s19, s19, 0
	s_add_u32 s46, s20, 0x100
	v_mov_b64_e32 v[0:1], 0
	s_addc_u32 s47, s21, 0
	s_mov_b32 s20, 0
	v_mov_b64_e32 v[2:3], 0
	v_mov_b64_e32 v[4:5], 0
	v_mov_b64_e32 v[6:7], 0
	v_mov_b64_e32 v[8:9], 0
	v_mov_b64_e32 v[10:11], 0
	v_mov_b64_e32 v[12:13], 0
	v_mov_b64_e32 v[14:15], 0
	v_mov_b64_e32 v[16:17], 0
	v_mov_b64_e32 v[18:19], 0
	v_mov_b64_e32 v[20:21], 0
	v_mov_b64_e32 v[22:23], 0
	v_mov_b64_e32 v[24:25], 0
	v_mov_b64_e32 v[26:27], 0
	v_mov_b64_e32 v[28:29], 0
	v_mov_b64_e32 v[30:31], 0
	v_mov_b64_e32 v[32:33], 0
	v_mov_b64_e32 v[34:35], 0
	v_mov_b64_e32 v[36:37], 0
	v_mov_b64_e32 v[38:39], 0
	v_mov_b64_e32 v[40:41], 0
	v_mov_b64_e32 v[42:43], 0
	v_mov_b64_e32 v[44:45], 0
	v_mov_b64_e32 v[46:47], 0
	v_mov_b64_e32 v[48:49], 0
	v_mov_b64_e32 v[50:51], 0
	v_mov_b64_e32 v[52:53], 0
	v_mov_b64_e32 v[54:55], 0
	v_mov_b64_e32 v[56:57], 0
	v_mov_b64_e32 v[58:59], 0
	v_mov_b64_e32 v[60:61], 0
	v_mov_b64_e32 v[62:63], 0
	v_mov_b64_e32 v[66:67], 0
	v_mov_b64_e32 v[68:69], 0
	v_mov_b64_e32 v[70:71], 0
	v_mov_b64_e32 v[72:73], 0
	v_mov_b64_e32 v[74:75], 0
	v_mov_b64_e32 v[76:77], 0
	v_mov_b64_e32 v[78:79], 0
	v_mov_b64_e32 v[80:81], 0
	v_mov_b64_e32 v[82:83], 0
	v_mov_b64_e32 v[84:85], 0
	v_mov_b64_e32 v[86:87], 0
	v_mov_b64_e32 v[88:89], 0
	v_mov_b64_e32 v[90:91], 0
	v_mov_b64_e32 v[92:93], 0
	v_mov_b64_e32 v[94:95], 0
	v_mov_b64_e32 v[96:97], 0
	v_mov_b64_e32 v[98:99], 0
	v_mov_b64_e32 v[100:101], 0
	v_mov_b64_e32 v[102:103], 0
	v_mov_b64_e32 v[104:105], 0
	v_mov_b64_e32 v[106:107], 0
	v_mov_b64_e32 v[108:109], 0
	v_mov_b64_e32 v[110:111], 0
	v_mov_b64_e32 v[112:113], 0
	v_mov_b64_e32 v[114:115], 0
	v_mov_b64_e32 v[116:117], 0
	v_mov_b64_e32 v[118:119], 0
	v_mov_b64_e32 v[120:121], 0
	v_mov_b64_e32 v[122:123], 0
	v_mov_b64_e32 v[124:125], 0
	v_mov_b64_e32 v[126:127], 0
	v_mov_b64_e32 v[128:129], 0

; template <class Epi, class Sched, bool ALIGN_EPI = false, bool SP2 = false>
; __device__ __forceinline__ void gemm_phase(PG8_LAS unsigned char* lds, const Gemm g, const Sched& S, const Epi& E) {
;     ...
;         const bool has_next = S.next(ui + 1, nxt);
;         const char* nA = has_next ? (const char*)g.A + (size_t)nxt.pm * tstepA + (size_t)S.kt0(nxt) * (BK * 2) : cA; const char* nB = has_next ? (const char*)g.Bt + (size_t)nxt.pn * tstepB + (size_t)S.kt0(nxt) * (BK * 2) : cB;
;         for (int t = 0; t < ntc; t += 2) {
;             const bool last = (t == ntc - 2);
;             const char* a1 = cA + (size_t)(t + 1) * kstep;
;             const char* a2 = last ? nA : cA + (size_t)(t + 2) * kstep; const char* b2 = last ? nB : cB + (size_t)(t + 2) * kstep;
;             const char* a3 = a2 + kstep; const char* b3 = b2 + kstep;
;     ...
;         for (int a = 0; a < 2; ++a)
; #pragma unroll
;             for (int b = 0; b < 2; ++b)
; #pragma unroll
;                 for (int m = 0; m < 4; ++m)
; #pragma unroll
;                     for (int n = 0; n < 2; ++n) acc[a][b][m][n] = (f32x4){0.f, 0.f, 0.f, 0.f};
;         cur = nxt; cA = nA; cB = nB; ++ui; ntc = S.ktn(cur, nt);
.LBB0_1185:
	s_ashr_i32 s15, s14, 31
	s_lshl_b64 s[18:19], s[14:15], 19
	s_add_u32 s18, s16, s18
	s_addc_u32 s19, s17, s19
	s_ashr_i32 s13, s12, 31
	s_lshl_b64 s[20:21], s[12:13], 19
	s_add_u32 s20, s27, s20
	v_mov_b32_e32 v125, 0
	s_addc_u32 s21, s28, s21
	s_andn2_b64 vcc, exec, s[8:9]
	v_mov_b32_e32 v124, v125
	v_mov_b32_e32 v123, v125
	v_mov_b32_e32 v122, v125
	v_mov_b32_e32 v129, v125
	v_mov_b32_e32 v128, v125
	v_mov_b32_e32 v127, v125
	v_mov_b32_e32 v126, v125
	v_mov_b32_e32 v113, v125
	v_mov_b32_e32 v112, v125
	v_mov_b32_e32 v111, v125
	v_mov_b32_e32 v110, v125
	v_mov_b32_e32 v109, v125
	v_mov_b32_e32 v108, v125
	v_mov_b32_e32 v107, v125
	v_mov_b32_e32 v106, v125
	v_mov_b32_e32 v97, v125
	v_mov_b32_e32 v96, v125
	v_mov_b32_e32 v95, v125
	v_mov_b32_e32 v94, v125
	v_mov_b32_e32 v93, v125
	v_mov_b32_e32 v92, v125
	v_mov_b32_e32 v91, v125
	v_mov_b32_e32 v90, v125
	v_mov_b32_e32 v81, v125
	v_mov_b32_e32 v80, v125
	v_mov_b32_e32 v79, v125
	v_mov_b32_e32 v78, v125
	v_mov_b32_e32 v77, v125
	v_mov_b32_e32 v76, v125
	v_mov_b32_e32 v75, v125
	v_mov_b32_e32 v74, v125
	v_mov_b32_e32 v121, v125
	v_mov_b32_e32 v120, v125
	v_mov_b32_e32 v119, v125
	v_mov_b32_e32 v118, v125
	v_mov_b32_e32 v117, v125
	v_mov_b32_e32 v116, v125
	v_mov_b32_e32 v115, v125
	v_mov_b32_e32 v114, v125
	v_mov_b32_e32 v105, v125
	v_mov_b32_e32 v104, v125
	v_mov_b32_e32 v103, v125
	v_mov_b32_e32 v102, v125
	v_mov_b32_e32 v101, v125
	v_mov_b32_e32 v100, v125
	v_mov_b32_e32 v99, v125
	v_mov_b32_e32 v98, v125
	s_waitcnt vmcnt(0)
	v_mov_b32_e32 v89, v125
	v_mov_b32_e32 v88, v125
	v_mov_b32_e32 v87, v125
	v_mov_b32_e32 v86, v125
	v_mov_b32_e32 v85, v125
	v_mov_b32_e32 v84, v125
	v_mov_b32_e32 v83, v125
	v_mov_b32_e32 v82, v125
	v_mov_b32_e32 v73, v125
	v_mov_b32_e32 v72, v125
	v_mov_b32_e32 v71, v125
	v_mov_b32_e32 v70, v125
	v_mov_b32_e32 v69, v125
	v_mov_b32_e32 v68, v125
	v_mov_b32_e32 v67, v125
	v_mov_b32_e32 v66, v125
	v_mov_b32_e32 v63, v125
	v_mov_b32_e32 v62, v125
	v_mov_b32_e32 v61, v125
	v_mov_b32_e32 v60, v125
	v_mov_b32_e32 v59, v125
	v_mov_b32_e32 v58, v125
	v_mov_b32_e32 v57, v125
	v_mov_b32_e32 v56, v125
	v_mov_b32_e32 v47, v125
	v_mov_b32_e32 v46, v125
	v_mov_b32_e32 v45, v125
	v_mov_b32_e32 v44, v125
	v_mov_b32_e32 v43, v125
	v_mov_b32_e32 v42, v125
	v_mov_b32_e32 v41, v125
	v_mov_b32_e32 v40, v125
	v_mov_b32_e32 v31, v125
	v_mov_b32_e32 v30, v125
	v_mov_b32_e32 v29, v125
	v_mov_b32_e32 v28, v125
	v_mov_b32_e32 v27, v125
	v_mov_b32_e32 v26, v125
	v_mov_b32_e32 v25, v125
	v_mov_b32_e32 v24, v125
	v_mov_b32_e32 v15, v125
	v_mov_b32_e32 v14, v125
	v_mov_b32_e32 v13, v125
	v_mov_b32_e32 v12, v125
	v_mov_b32_e32 v11, v125
	v_mov_b32_e32 v10, v125
	v_mov_b32_e32 v9, v125
	v_mov_b32_e32 v8, v125
	v_mov_b32_e32 v55, v125
	v_mov_b32_e32 v54, v125
	v_mov_b32_e32 v53, v125
	v_mov_b32_e32 v52, v125
	v_mov_b32_e32 v51, v125
	v_mov_b32_e32 v50, v125
	v_mov_b32_e32 v49, v125
	v_mov_b32_e32 v48, v125
	v_mov_b32_e32 v39, v125
	v_mov_b32_e32 v38, v125
	v_mov_b32_e32 v37, v125
	v_mov_b32_e32 v36, v125
	v_mov_b32_e32 v35, v125
	v_mov_b32_e32 v34, v125
	v_mov_b32_e32 v33, v125
	v_mov_b32_e32 v32, v125
	v_mov_b32_e32 v23, v125
	v_mov_b32_e32 v22, v125
	v_mov_b32_e32 v21, v125
	v_mov_b32_e32 v20, v125
	v_mov_b32_e32 v19, v125
	v_mov_b32_e32 v18, v125
	v_mov_b32_e32 v17, v125
	v_mov_b32_e32 v16, v125
	v_mov_b32_e32 v7, v125
	v_mov_b32_e32 v6, v125
	v_mov_b32_e32 v5, v125
	v_mov_b32_e32 v4, v125
	v_mov_b32_e32 v3, v125
	v_mov_b32_e32 v2, v125
	v_mov_b32_e32 v1, v125
	v_mov_b32_e32 v0, v125
	s_cbranch_vccnz .LBB0_1188
	s_and_b64 s[24:25], s[6:7], exec
	s_cselect_b32 s13, s19, s5
	s_cselect_b32 s15, s18, s4
	s_cselect_b32 s45, s21, s23
	s_cselect_b32 s46, s20, s22
	s_add_u32 s4, s4, 0x40080
	s_addc_u32 s5, s5, 0
	s_add_u32 s47, s22, 0x100
	v_mov_b64_e32 v[0:1], 0
	s_addc_u32 s48, s23, 0
	s_mov_b32 s22, 0
	v_mov_b64_e32 v[2:3], 0
	v_mov_b64_e32 v[4:5], 0
	v_mov_b64_e32 v[6:7], 0
	v_mov_b64_e32 v[8:9], 0
	v_mov_b64_e32 v[10:11], 0
	v_mov_b64_e32 v[12:13], 0
	v_mov_b64_e32 v[14:15], 0
	v_mov_b64_e32 v[16:17], 0
	v_mov_b64_e32 v[18:19], 0
	v_mov_b64_e32 v[20:21], 0
	v_mov_b64_e32 v[22:23], 0
	v_mov_b64_e32 v[24:25], 0
	v_mov_b64_e32 v[26:27], 0
	v_mov_b64_e32 v[28:29], 0
	v_mov_b64_e32 v[30:31], 0
	v_mov_b64_e32 v[32:33], 0
	v_mov_b64_e32 v[34:35], 0
	v_mov_b64_e32 v[36:37], 0
	v_mov_b64_e32 v[38:39], 0
	v_mov_b64_e32 v[40:41], 0
	v_mov_b64_e32 v[42:43], 0
	v_mov_b64_e32 v[44:45], 0
	v_mov_b64_e32 v[46:47], 0
	v_mov_b64_e32 v[48:49], 0
	v_mov_b64_e32 v[50:51], 0
	v_mov_b64_e32 v[52:53], 0
	v_mov_b64_e32 v[54:55], 0
	v_mov_b64_e32 v[56:57], 0
	v_mov_b64_e32 v[58:59], 0
	v_mov_b64_e32 v[60:61], 0
	v_mov_b64_e32 v[62:63], 0
	v_mov_b64_e32 v[66:67], 0
	v_mov_b64_e32 v[68:69], 0
	v_mov_b64_e32 v[70:71], 0
	v_mov_b64_e32 v[72:73], 0
	v_mov_b64_e32 v[74:75], 0
	v_mov_b64_e32 v[76:77], 0
	v_mov_b64_e32 v[78:79], 0
	v_mov_b64_e32 v[80:81], 0
	v_mov_b64_e32 v[82:83], 0
	v_mov_b64_e32 v[84:85], 0
	v_mov_b64_e32 v[86:87], 0
	v_mov_b64_e32 v[88:89], 0
	v_mov_b64_e32 v[90:91], 0
	v_mov_b64_e32 v[92:93], 0
	v_mov_b64_e32 v[94:95], 0
	v_mov_b64_e32 v[96:97], 0
	v_mov_b64_e32 v[98:99], 0
	v_mov_b64_e32 v[100:101], 0
	v_mov_b64_e32 v[102:103], 0
	v_mov_b64_e32 v[104:105], 0
	v_mov_b64_e32 v[106:107], 0
	v_mov_b64_e32 v[108:109], 0
	v_mov_b64_e32 v[110:111], 0
	v_mov_b64_e32 v[112:113], 0
	v_mov_b64_e32 v[114:115], 0
	v_mov_b64_e32 v[116:117], 0
	v_mov_b64_e32 v[118:119], 0
	v_mov_b64_e32 v[120:121], 0
	v_mov_b64_e32 v[122:123], 0
	v_mov_b64_e32 v[124:125], 0
	v_mov_b64_e32 v[126:127], 0
	v_mov_b64_e32 v[128:129], 0
